# attention loop: conservative vmcnt wait moved from step A QK to step B LDS stores; progressive lgkmcnt in step A
# baseline (speedup 1.0000x reference)
.LBB0_1084:
	ds_read_b128 v[68:71], v234
	ds_read_b128 v[100:103], v234 offset:32
	ds_read_b128 v[72:75], v234 offset:8704
	ds_read_b128 v[104:107], v234 offset:8736
	ds_read_b128 v[108:111], v234 offset:64
	ds_read_b128 v[112:115], v234 offset:96
	ds_read_b128 v[116:119], v234 offset:8768
	ds_read_b128 v[120:123], v234 offset:8800
	s_waitcnt lgkmcnt(7)
	v_mfma_f32_32x32x16_bf16 v[84:99], v[68:71], v[140:143], 0
	ds_read_b64_tr_b16 v[176:177], v235 offset:17408
	ds_read_b64_tr_b16 v[172:173], v235 offset:17472
	ds_read_b64_tr_b16 v[168:169], v235 offset:17536
	ds_read_b64_tr_b16 v[164:165], v235 offset:17600
	ds_read_b64_tr_b16 v[178:179], v235 offset:19968
	ds_read_b64_tr_b16 v[174:175], v235 offset:20032
	ds_read_b64_tr_b16 v[170:171], v235 offset:20096
	ds_read_b64_tr_b16 v[166:167], v235 offset:20160
	s_waitcnt lgkmcnt(13)
	v_mfma_f32_32x32x16_bf16 v[68:83], v[72:75], v[140:143], 0
	v_mfma_f32_32x32x16_bf16 v[84:99], v[100:103], v[132:135], v[84:99]
	s_waitcnt lgkmcnt(12)
	v_mfma_f32_32x32x16_bf16 v[68:83], v[104:107], v[132:135], v[68:83]
	s_waitcnt lgkmcnt(11)
	v_mfma_f32_32x32x16_bf16 v[84:99], v[108:111], v[136:139], v[84:99]
	s_waitcnt lgkmcnt(9)
	v_mfma_f32_32x32x16_bf16 v[68:83], v[116:119], v[136:139], v[68:83]
	v_mfma_f32_32x32x16_bf16 v[84:99], v[112:115], v[144:147], v[84:99]
	s_waitcnt lgkmcnt(8)
	v_mfma_f32_32x32x16_bf16 v[68:83], v[120:123], v[144:147], v[68:83]
	s_cmp_lt_i32 s52, s50
	s_cbranch_scc1 .LBB0_1150
	v_cmp_lt_i32_e32 vcc, -1, v67
	v_mov_b32_e32 v100, 0xf149f2ca
	v_mov_b32_e32 v116, 0xf149f2ca
	s_and_saveexec_b64 s[34:35], vcc
	s_cbranch_execz .LBB0_1087
	v_min_u32_e32 v0, 0x7f, v67
	v_lshl_add_u32 v0, v0, 2, 0
	v_add_u32_e32 v0, 0x12800, v0
	ds_read_b32 v0, v0
	s_waitcnt lgkmcnt(0)
	v_add_f32_e32 v116, v84, v0

.LBB0_1152:
	v_sub_f32_e32 v0, v91, v66
	v_sub_f32_e32 v90, v90, v66
	v_sub_f32_e32 v89, v89, v66
	v_sub_f32_e32 v88, v88, v66
	v_sub_f32_e32 v87, v87, v66
	v_sub_f32_e32 v86, v86, v66
	v_sub_f32_e32 v85, v85, v66
	v_sub_f32_e32 v84, v84, v66
	v_exp_f32_e32 v196, v84
	v_exp_f32_e32 v197, v85
	v_exp_f32_e32 v200, v86
	v_exp_f32_e32 v201, v87
	v_exp_f32_e32 v198, v88
	v_exp_f32_e32 v199, v89
	v_exp_f32_e32 v194, v90
	v_exp_f32_e32 v195, v0
	v_cvt_pk_bf16_f32 v84, v196, v197
	v_cvt_pk_bf16_f32 v85, v200, v201
	v_cvt_pk_bf16_f32 v86, v198, v199
	v_cvt_pk_bf16_f32 v87, v194, v195
	v_sub_f32_e32 v0, v99, v66
	v_sub_f32_e32 v88, v98, v66
	s_waitcnt lgkmcnt(3)
	v_mfma_f32_32x32x16_bf16 v[50:65], v[176:179], v[84:87], v[50:65]
	v_sub_f32_e32 v89, v97, v66
	v_sub_f32_e32 v90, v96, v66
	v_sub_f32_e32 v91, v95, v66
	v_sub_f32_e32 v94, v94, v66
	v_sub_f32_e32 v93, v93, v66
	v_sub_f32_e32 v92, v92, v66
	v_exp_f32_e32 v204, v92
	s_waitcnt lgkmcnt(2)
	v_mfma_f32_32x32x16_bf16 v[34:49], v[172:175], v[84:87], v[34:49]
	v_exp_f32_e32 v205, v93
	v_exp_f32_e32 v208, v94
	v_exp_f32_e32 v209, v91
	v_exp_f32_e32 v202, v90
	v_exp_f32_e32 v203, v89
	v_exp_f32_e32 v206, v88
	v_exp_f32_e32 v207, v0
	s_waitcnt lgkmcnt(1)
	v_mfma_f32_32x32x16_bf16 v[18:33], v[168:171], v[84:87], v[18:33]
	ds_read_b64_tr_b16 v[92:93], v235 offset:22528
	ds_read_b64_tr_b16 v[94:95], v235 offset:25088
	v_cvt_pk_bf16_f32 v88, v204, v205
	v_cvt_pk_bf16_f32 v89, v208, v209
	v_cvt_pk_bf16_f32 v90, v202, v203
	v_cvt_pk_bf16_f32 v91, v206, v207
	v_sub_f32_e32 v0, v75, v66
	v_sub_f32_e32 v74, v74, v66
	s_waitcnt lgkmcnt(2)
	v_mfma_f32_32x32x16_bf16 v[2:17], v[164:167], v[84:87], v[2:17]
	ds_read_b64_tr_b16 v[84:85], v235 offset:22592
	ds_read_b64_tr_b16 v[96:97], v235 offset:22656
	ds_read_b64_tr_b16 v[100:101], v235 offset:22720
	ds_read_b64_tr_b16 v[86:87], v235 offset:25152
	ds_read_b64_tr_b16 v[98:99], v235 offset:25216
	ds_read_b64_tr_b16 v[102:103], v235 offset:25280
	v_sub_f32_e32 v73, v73, v66
	v_sub_f32_e32 v72, v72, v66
	v_sub_f32_e32 v71, v71, v66
	v_sub_f32_e32 v70, v70, v66
	v_sub_f32_e32 v69, v69, v66
	v_sub_f32_e32 v68, v68, v66
	s_waitcnt lgkmcnt(6)
	v_mfma_f32_32x32x16_bf16 v[50:65], v[92:95], v[88:91], v[50:65]
	v_exp_f32_e32 v214, v68
	v_exp_f32_e32 v215, v69
	v_exp_f32_e32 v216, v70
	v_exp_f32_e32 v217, v71
	v_exp_f32_e32 v210, v72
	v_exp_f32_e32 v211, v73
	v_exp_f32_e32 v212, v74
	s_waitcnt lgkmcnt(2)
	v_mfma_f32_32x32x16_bf16 v[34:49], v[84:87], v[88:91], v[34:49]
	v_exp_f32_e32 v213, v0
	ds_read_b64_tr_b16 v[72:73], v235 offset:27648
	ds_read_b64_tr_b16 v[74:75], v235 offset:30208
	v_cvt_pk_bf16_f32 v68, v214, v215
	v_cvt_pk_bf16_f32 v69, v216, v217
	v_cvt_pk_bf16_f32 v70, v210, v211
	v_cvt_pk_bf16_f32 v71, v212, v213
	v_sub_f32_e32 v0, v83, v66
	s_waitcnt lgkmcnt(3)
	v_mfma_f32_32x32x16_bf16 v[18:33], v[96:99], v[88:91], v[18:33]
	v_sub_f32_e32 v78, v78, v66
	v_sub_f32_e32 v77, v77, v66
	v_sub_f32_e32 v76, v76, v66
	v_exp_f32_e32 v222, v76
	v_exp_f32_e32 v223, v77
	v_exp_f32_e32 v224, v78
	v_exp_f32_e32 v221, v0
	s_waitcnt lgkmcnt(2)
	v_mfma_f32_32x32x16_bf16 v[2:17], v[100:103], v[88:91], v[2:17]
	ds_read_b64_tr_b16 v[84:85], v235 offset:27712
	ds_read_b64_tr_b16 v[88:89], v235 offset:27776
	ds_read_b64_tr_b16 v[92:93], v235 offset:27840
	ds_read_b64_tr_b16 v[86:87], v235 offset:30272
	ds_read_b64_tr_b16 v[90:91], v235 offset:30336
	ds_read_b64_tr_b16 v[94:95], v235 offset:30400
	s_andn2_b64 vcc, exec, s[30:31]
	s_waitcnt lgkmcnt(6)
	v_mfma_f32_32x32x16_bf16 v[50:65], v[72:75], v[68:71], v[50:65]
	v_sub_f32_e32 v72, v82, v66
	v_sub_f32_e32 v73, v81, v66
	v_sub_f32_e32 v74, v80, v66
	v_sub_f32_e32 v75, v79, v66
	v_exp_f32_e32 v225, v75
	v_exp_f32_e32 v218, v74
	v_exp_f32_e32 v219, v73
	s_waitcnt lgkmcnt(2)
	v_mfma_f32_32x32x16_bf16 v[34:49], v[84:87], v[68:71], v[34:49]
	v_exp_f32_e32 v220, v72
	ds_read_b64_tr_b16 v[76:77], v235 offset:32768
	ds_read_b64_tr_b16 v[78:79], v235 offset:35328
	v_cvt_pk_bf16_f32 v72, v222, v223
	v_cvt_pk_bf16_f32 v73, v224, v225
	v_cvt_pk_bf16_f32 v74, v218, v219
	v_cvt_pk_bf16_f32 v75, v220, v221
	s_waitcnt lgkmcnt(3)
	v_mfma_f32_32x32x16_bf16 v[18:33], v[88:91], v[68:71], v[18:33]
	s_waitcnt lgkmcnt(2)
	v_mfma_f32_32x32x16_bf16 v[2:17], v[92:95], v[68:71], v[2:17]
	ds_read_b64_tr_b16 v[68:69], v235 offset:32832
	ds_read_b64_tr_b16 v[80:81], v235 offset:32896
	ds_read_b64_tr_b16 v[84:85], v235 offset:32960
	ds_read_b64_tr_b16 v[70:71], v235 offset:35392
	ds_read_b64_tr_b16 v[82:83], v235 offset:35456
	ds_read_b64_tr_b16 v[86:87], v235 offset:35520
	s_waitcnt lgkmcnt(0)
	s_barrier
	s_waitcnt lgkmcnt(6)
	v_mfma_f32_32x32x16_bf16 v[50:65], v[76:79], v[72:75], v[50:65]
	s_waitcnt lgkmcnt(2)
	v_mfma_f32_32x32x16_bf16 v[34:49], v[68:71], v[72:75], v[34:49]
	s_waitcnt lgkmcnt(1)
	v_mfma_f32_32x32x16_bf16 v[18:33], v[80:83], v[72:75], v[18:33]
	s_waitcnt lgkmcnt(0)
	v_mfma_f32_32x32x16_bf16 v[2:17], v[84:87], v[72:75], v[2:17]
	s_cbranch_vccnz .LBB0_1154
	s_waitcnt vmcnt(3)
	ds_write_b128 v226, v[148:151]
	s_waitcnt vmcnt(2)
	ds_write_b128 v227, v[152:155]
	s_waitcnt vmcnt(1)
	ds_write_b128 v232, v[156:159] offset:17408
	s_waitcnt vmcnt(0)
	ds_write_b128 v233, v[160:163] offset:17408

.LBB0_2344:
	ds_read_b128 v[68:71], v234
	ds_read_b128 v[100:103], v234 offset:32
	ds_read_b128 v[72:75], v234 offset:8704
	ds_read_b128 v[104:107], v234 offset:8736
	ds_read_b128 v[108:111], v234 offset:64
	ds_read_b128 v[112:115], v234 offset:96
	ds_read_b128 v[116:119], v234 offset:8768
	ds_read_b128 v[120:123], v234 offset:8800
	s_waitcnt lgkmcnt(7)
	v_mfma_f32_32x32x16_bf16 v[84:99], v[68:71], v[140:143], 0
	ds_read_b64_tr_b16 v[176:177], v235 offset:17408
	ds_read_b64_tr_b16 v[172:173], v235 offset:17472
	ds_read_b64_tr_b16 v[168:169], v235 offset:17536
	ds_read_b64_tr_b16 v[164:165], v235 offset:17600
	ds_read_b64_tr_b16 v[178:179], v235 offset:19968
	ds_read_b64_tr_b16 v[174:175], v235 offset:20032
	ds_read_b64_tr_b16 v[170:171], v235 offset:20096
	ds_read_b64_tr_b16 v[166:167], v235 offset:20160
	s_waitcnt lgkmcnt(13)
	v_mfma_f32_32x32x16_bf16 v[68:83], v[72:75], v[140:143], 0
	v_mfma_f32_32x32x16_bf16 v[84:99], v[100:103], v[132:135], v[84:99]
	s_waitcnt lgkmcnt(12)
	v_mfma_f32_32x32x16_bf16 v[68:83], v[104:107], v[132:135], v[68:83]
	s_waitcnt lgkmcnt(11)
	v_mfma_f32_32x32x16_bf16 v[84:99], v[108:111], v[136:139], v[84:99]
	s_waitcnt lgkmcnt(9)
	v_mfma_f32_32x32x16_bf16 v[68:83], v[116:119], v[136:139], v[68:83]
	v_mfma_f32_32x32x16_bf16 v[84:99], v[112:115], v[144:147], v[84:99]
	s_waitcnt lgkmcnt(8)
	v_mfma_f32_32x32x16_bf16 v[68:83], v[120:123], v[144:147], v[68:83]
	s_cmp_lt_i32 s69, s67
	s_cbranch_scc1 .LBB0_2410
	v_cmp_lt_i32_e32 vcc, -1, v67
	v_mov_b32_e32 v100, 0xf149f2ca
	v_mov_b32_e32 v116, 0xf149f2ca
	s_and_saveexec_b64 s[40:41], vcc
	s_cbranch_execz .LBB0_2347
	v_min_u32_e32 v0, 0x7f, v67
	v_lshl_add_u32 v0, v0, 2, 0
	v_add_u32_e32 v0, 0x12800, v0
	ds_read_b32 v0, v0
	s_waitcnt lgkmcnt(0)
	v_add_f32_e32 v116, v84, v0

.LBB0_2412:
	v_sub_f32_e32 v0, v91, v66
	v_sub_f32_e32 v90, v90, v66
	v_sub_f32_e32 v89, v89, v66
	v_sub_f32_e32 v88, v88, v66
	v_sub_f32_e32 v87, v87, v66
	v_sub_f32_e32 v86, v86, v66
	v_sub_f32_e32 v85, v85, v66
	v_sub_f32_e32 v84, v84, v66
	v_exp_f32_e32 v196, v84
	v_exp_f32_e32 v197, v85
	v_exp_f32_e32 v200, v86
	v_exp_f32_e32 v201, v87
	v_exp_f32_e32 v198, v88
	v_exp_f32_e32 v199, v89
	v_exp_f32_e32 v194, v90
	v_exp_f32_e32 v195, v0
	v_cvt_pk_bf16_f32 v84, v196, v197
	v_cvt_pk_bf16_f32 v85, v200, v201
	v_cvt_pk_bf16_f32 v86, v198, v199
	v_cvt_pk_bf16_f32 v87, v194, v195
	v_sub_f32_e32 v0, v99, v66
	v_sub_f32_e32 v88, v98, v66
	s_waitcnt lgkmcnt(3)
	v_mfma_f32_32x32x16_bf16 v[50:65], v[176:179], v[84:87], v[50:65]
	v_sub_f32_e32 v89, v97, v66
	v_sub_f32_e32 v90, v96, v66
	v_sub_f32_e32 v91, v95, v66
	v_sub_f32_e32 v94, v94, v66
	v_sub_f32_e32 v93, v93, v66
	v_sub_f32_e32 v92, v92, v66
	v_exp_f32_e32 v206, v92
	s_waitcnt lgkmcnt(2)
	v_mfma_f32_32x32x16_bf16 v[34:49], v[172:175], v[84:87], v[34:49]
	v_exp_f32_e32 v207, v93
	v_exp_f32_e32 v208, v94
	v_exp_f32_e32 v209, v91
	v_exp_f32_e32 v202, v90
	v_exp_f32_e32 v203, v89
	v_exp_f32_e32 v204, v88
	v_exp_f32_e32 v205, v0
	s_waitcnt lgkmcnt(1)
	v_mfma_f32_32x32x16_bf16 v[18:33], v[168:171], v[84:87], v[18:33]
	ds_read_b64_tr_b16 v[92:93], v235 offset:22528
	ds_read_b64_tr_b16 v[94:95], v235 offset:25088
	v_cvt_pk_bf16_f32 v88, v206, v207
	v_cvt_pk_bf16_f32 v89, v208, v209
	v_cvt_pk_bf16_f32 v90, v202, v203
	v_cvt_pk_bf16_f32 v91, v204, v205
	v_sub_f32_e32 v0, v75, v66
	v_sub_f32_e32 v74, v74, v66
	s_waitcnt lgkmcnt(2)
	v_mfma_f32_32x32x16_bf16 v[2:17], v[164:167], v[84:87], v[2:17]
	ds_read_b64_tr_b16 v[84:85], v235 offset:22592
	ds_read_b64_tr_b16 v[96:97], v235 offset:22656
	ds_read_b64_tr_b16 v[100:101], v235 offset:22720
	ds_read_b64_tr_b16 v[86:87], v235 offset:25152
	ds_read_b64_tr_b16 v[98:99], v235 offset:25216
	ds_read_b64_tr_b16 v[102:103], v235 offset:25280
	v_sub_f32_e32 v73, v73, v66
	v_sub_f32_e32 v72, v72, v66
	v_sub_f32_e32 v71, v71, v66
	v_sub_f32_e32 v70, v70, v66
	v_sub_f32_e32 v69, v69, v66
	v_sub_f32_e32 v68, v68, v66
	s_waitcnt lgkmcnt(6)
	v_mfma_f32_32x32x16_bf16 v[50:65], v[92:95], v[88:91], v[50:65]
	v_exp_f32_e32 v214, v68
	v_exp_f32_e32 v215, v69
	v_exp_f32_e32 v216, v70
	v_exp_f32_e32 v217, v71
	v_exp_f32_e32 v212, v72
	v_exp_f32_e32 v213, v73
	v_exp_f32_e32 v210, v74
	s_waitcnt lgkmcnt(2)
	v_mfma_f32_32x32x16_bf16 v[34:49], v[84:87], v[88:91], v[34:49]
	v_exp_f32_e32 v211, v0
	ds_read_b64_tr_b16 v[72:73], v235 offset:27648
	ds_read_b64_tr_b16 v[74:75], v235 offset:30208
	v_cvt_pk_bf16_f32 v68, v214, v215
	v_cvt_pk_bf16_f32 v69, v216, v217
	v_cvt_pk_bf16_f32 v70, v212, v213
	v_cvt_pk_bf16_f32 v71, v210, v211
	v_sub_f32_e32 v0, v83, v66
	s_waitcnt lgkmcnt(3)
	v_mfma_f32_32x32x16_bf16 v[18:33], v[96:99], v[88:91], v[18:33]
	v_sub_f32_e32 v78, v78, v66
	v_sub_f32_e32 v77, v77, v66
	v_sub_f32_e32 v76, v76, v66
	v_exp_f32_e32 v222, v76
	v_exp_f32_e32 v223, v77
	v_exp_f32_e32 v224, v78
	v_exp_f32_e32 v219, v0
	s_waitcnt lgkmcnt(2)
	v_mfma_f32_32x32x16_bf16 v[2:17], v[100:103], v[88:91], v[2:17]
	ds_read_b64_tr_b16 v[84:85], v235 offset:27712
	ds_read_b64_tr_b16 v[88:89], v235 offset:27776
	ds_read_b64_tr_b16 v[92:93], v235 offset:27840
	ds_read_b64_tr_b16 v[86:87], v235 offset:30272
	ds_read_b64_tr_b16 v[90:91], v235 offset:30336
	ds_read_b64_tr_b16 v[94:95], v235 offset:30400
	s_andn2_b64 vcc, exec, s[38:39]
	s_waitcnt lgkmcnt(6)
	v_mfma_f32_32x32x16_bf16 v[50:65], v[72:75], v[68:71], v[50:65]
	v_sub_f32_e32 v72, v82, v66
	v_sub_f32_e32 v73, v81, v66
	v_sub_f32_e32 v74, v80, v66
	v_sub_f32_e32 v75, v79, v66
	v_exp_f32_e32 v225, v75
	v_exp_f32_e32 v220, v74
	v_exp_f32_e32 v221, v73
	s_waitcnt lgkmcnt(2)
	v_mfma_f32_32x32x16_bf16 v[34:49], v[84:87], v[68:71], v[34:49]
	v_exp_f32_e32 v218, v72
	ds_read_b64_tr_b16 v[76:77], v235 offset:32768
	ds_read_b64_tr_b16 v[78:79], v235 offset:35328
	v_cvt_pk_bf16_f32 v72, v222, v223
	v_cvt_pk_bf16_f32 v73, v224, v225
	v_cvt_pk_bf16_f32 v74, v220, v221
	v_cvt_pk_bf16_f32 v75, v218, v219
	s_waitcnt lgkmcnt(3)
	v_mfma_f32_32x32x16_bf16 v[18:33], v[88:91], v[68:71], v[18:33]
	s_waitcnt lgkmcnt(2)
	v_mfma_f32_32x32x16_bf16 v[2:17], v[92:95], v[68:71], v[2:17]
	ds_read_b64_tr_b16 v[68:69], v235 offset:32832
	ds_read_b64_tr_b16 v[80:81], v235 offset:32896
	ds_read_b64_tr_b16 v[84:85], v235 offset:32960
	ds_read_b64_tr_b16 v[70:71], v235 offset:35392
	ds_read_b64_tr_b16 v[82:83], v235 offset:35456
	ds_read_b64_tr_b16 v[86:87], v235 offset:35520
	s_waitcnt lgkmcnt(0)
	s_barrier
	s_waitcnt lgkmcnt(6)
	v_mfma_f32_32x32x16_bf16 v[50:65], v[76:79], v[72:75], v[50:65]
	s_waitcnt lgkmcnt(2)
	v_mfma_f32_32x32x16_bf16 v[34:49], v[68:71], v[72:75], v[34:49]
	s_waitcnt lgkmcnt(1)
	v_mfma_f32_32x32x16_bf16 v[18:33], v[80:83], v[72:75], v[18:33]
	s_waitcnt lgkmcnt(0)
	v_mfma_f32_32x32x16_bf16 v[2:17], v[84:87], v[72:75], v[2:17]
	s_cbranch_vccnz .LBB0_2414
	s_waitcnt vmcnt(3)
	ds_write_b128 v227, v[148:151]
	s_waitcnt vmcnt(2)
	ds_write_b128 v228, v[152:155]
	s_waitcnt vmcnt(1)
	ds_write_b128 v232, v[156:159] offset:17408
	s_waitcnt vmcnt(0)
	ds_write_b128 v233, v[160:163] offset:17408
